# v9 + RELU2 epilogue canonicalize ops removed, v_mov_b64 acc zeroing, tile-start vmcnt(0) drain removed, redundant setprio 0/1 pairs inside GEMM MFMA blocks removed
# speedup vs baseline: 1.0152x; 1.0092x over previous
; #define PG8_STAGE(bufoff, gbase, voff) do { _Pragma("unroll") for (int _i = 0; _i < 2; ++_i) \
;     __builtin_amdgcn_global_load_lds((const unsigned*)((const char*)(gbase) + (voff)[_i]), (LAS unsigned*)(lds + (bufoff) + ldsw + _i * 8192), 16, 0, 0); } while (0)
; #define PG8_LDA(dst, b, h) do { _Pragma("unroll") for (int m = 0; m < 4; ++m) _Pragma("unroll") for (int k = 0; k < 2; ++k) dst[m][k] = *(const LAS bf16x8*)(lds + PG8_SA(b, h) + aoff + m * 2048 + k * 1024); } while (0)
; #define PG8_LDB(dst, b, h) do { _Pragma("unroll") for (int n = 0; n < 2; ++n) _Pragma("unroll") for (int k = 0; k < 2; ++k) dst[n][k] = *(const LAS bf16x8*)(lds + PG8_SB(b, h) + boff + n * 2048 + k * 1024); } while (0)
; #define PG8_MMA(ai, bj, At, Bt) do { __builtin_amdgcn_s_setprio(1); _Pragma("unroll") for (int m = 0; m < 4; ++m) _Pragma("unroll") for (int n = 0; n < 2; ++n) _Pragma("unroll") for (int k = 0; k < 2; ++k) \
;     acc[ai][bj][m][n] = __builtin_amdgcn_mfma_f32_16x16x32_bf16(Bt[n][k], At[m][k], acc[ai][bj][m][n], 0, 0, 0); __builtin_amdgcn_s_setprio(0); } while (0)
; #define PG8_WAIT_V(n) asm volatile("s_waitcnt vmcnt(" #n ")" ::: "memory")
; #define PG8_WAIT_L(n) asm volatile("s_waitcnt lgkmcnt(" #n ")" ::: "memory")
; DI void gemm_phase(const GemmDesc& g, LAS unsigned char* lds) {
;     ...
;     const bool has_next = tile_next(ui + 1, G, cb, nM, nN, npm, npn);
;     const char* nA = has_next ? (const char*)g.A + (size_t)npm * tstep : cA; const char* nB = has_next ? (const char*)g.Bt + (size_t)npn * tstep : cB;
;     for (int t = 0; t < nt; t += 2) {
;       const bool last = (t == nt - 2);
;       const char* a1 = cA + (size_t)(t + 1) * kstep;
;       const char* a2 = last ? nA : cA + (size_t)(t + 2) * kstep; const char* b2 = last ? nB : cB + (size_t)(t + 2) * kstep;
;       const char* a3 = a2 + kstep; const char* b3 = b2 + kstep;
;       PG8_LDB(B0, 0, 0); PG8_LDB(B1, 0, 1); PG8_SCHED; PG8_LDA(At, 0, 0); PG8_STAGE(PG8_SA(1, 1), a1 + hstep, voffA);
;       PG8_WAIT_V(8); PG8_WAIT_L(0); PG8_BAR; PG8_MMA(0, 0, At, B0); PG8_MMA(0, 1, At, B1); PG8_BAR; PG8_SCHED;
;     ...
; #pragma unroll
;     for (int a = 0; a < 2; ++a)
; #pragma unroll
;       for (int b = 0; b < 2; ++b)
; #pragma unroll
;         for (int m = 0; m < 4; ++m)
; #pragma unroll
;           for (int n = 0; n < 2; ++n) acc[a][b][m][n] = (f32x4){0.f, 0.f, 0.f, 0.f};
;     cpm = npm; cpn = npn; cA = nA; cB = nB; ++ui;
.LBB0_131:
	s_add_u32 s46, s46, 0x100
	s_addc_u32 s47, s47, 0
	s_add_u32 s26, s48, 0x80
	s_addc_u32 s27, s49, 0
	s_mov_b32 s44, 0
	v_mov_b64_e32 v[0:1], 0
	v_mov_b64_e32 v[2:3], 0
	v_mov_b64_e32 v[4:5], 0
	v_mov_b64_e32 v[6:7], 0
	v_mov_b64_e32 v[8:9], 0
	v_mov_b64_e32 v[10:11], 0
	v_mov_b64_e32 v[12:13], 0
	v_mov_b64_e32 v[14:15], 0
	v_mov_b64_e32 v[16:17], 0
	v_mov_b64_e32 v[18:19], 0
	v_mov_b64_e32 v[20:21], 0
	v_mov_b64_e32 v[22:23], 0
	v_mov_b64_e32 v[24:25], 0
	v_mov_b64_e32 v[26:27], 0
	v_mov_b64_e32 v[28:29], 0
	v_mov_b64_e32 v[30:31], 0
	v_mov_b64_e32 v[32:33], 0
	v_mov_b64_e32 v[34:35], 0
	v_mov_b64_e32 v[36:37], 0
	v_mov_b64_e32 v[38:39], 0
	v_mov_b64_e32 v[40:41], 0
	v_mov_b64_e32 v[42:43], 0
	v_mov_b64_e32 v[44:45], 0
	v_mov_b64_e32 v[46:47], 0
	v_mov_b64_e32 v[48:49], 0
	v_mov_b64_e32 v[50:51], 0
	v_mov_b64_e32 v[52:53], 0
	v_mov_b64_e32 v[54:55], 0
	v_mov_b64_e32 v[56:57], 0
	v_mov_b64_e32 v[58:59], 0
	v_mov_b64_e32 v[60:61], 0
	v_mov_b64_e32 v[62:63], 0
	v_mov_b64_e32 v[64:65], 0
	v_mov_b64_e32 v[66:67], 0
	v_mov_b64_e32 v[68:69], 0
	v_mov_b64_e32 v[70:71], 0
	v_mov_b64_e32 v[72:73], 0
	v_mov_b64_e32 v[74:75], 0
	v_mov_b64_e32 v[76:77], 0
	v_mov_b64_e32 v[78:79], 0
	v_mov_b64_e32 v[80:81], 0
	v_mov_b64_e32 v[82:83], 0
	v_mov_b64_e32 v[84:85], 0
	v_mov_b64_e32 v[86:87], 0
	v_mov_b64_e32 v[88:89], 0
	v_mov_b64_e32 v[90:91], 0
	v_mov_b64_e32 v[92:93], 0
	v_mov_b64_e32 v[94:95], 0
	v_mov_b64_e32 v[96:97], 0
	v_mov_b64_e32 v[98:99], 0
	v_mov_b64_e32 v[100:101], 0
	v_mov_b64_e32 v[102:103], 0
	v_mov_b64_e32 v[104:105], 0
	v_mov_b64_e32 v[106:107], 0
	v_mov_b64_e32 v[108:109], 0
	v_mov_b64_e32 v[110:111], 0
	v_mov_b64_e32 v[112:113], 0
	v_mov_b64_e32 v[114:115], 0
	v_mov_b64_e32 v[116:117], 0
	v_mov_b64_e32 v[118:119], 0
	v_mov_b64_e32 v[120:121], 0
	v_mov_b64_e32 v[122:123], 0
	v_mov_b64_e32 v[124:125], 0
	v_mov_b64_e32 v[126:127], 0
.LBB0_132:
	s_add_i32 s48, s44, 2
	s_add_u32 s49, s26, 0x80
	s_addc_u32 s45, s27, 0
	s_add_i32 s51, 0, 0x10000
	s_cmp_eq_u32 s94, s44
	s_cselect_b32 s45, s63, s45
	s_cselect_b32 s44, s62, s49
	s_cselect_b32 s87, s1, s47
	s_cselect_b32 s86, s0, s46
	s_add_i32 s49, 0, 0x14000
	v_add_u32_e32 v140, s51, v219
	v_add_u32_e32 v148, s49, v219
	ds_read_b128 v[128:131], v140
	ds_read_b128 v[132:135], v140 offset:1024
	ds_read_b128 v[136:139], v140 offset:2048
	ds_read_b128 v[140:143], v140 offset:3072
	ds_read_b128 v[164:167], v148
	ds_read_b128 v[168:171], v148 offset:1024
	ds_read_b128 v[172:175], v148 offset:2048
	ds_read_b128 v[176:179], v148 offset:3072
	v_lshl_add_u64 v[212:213], s[26:27], 0, v[162:163]
	s_add_i32 m0, s73, 0xc000
	ds_read_b128 v[180:183], v228
	ds_read_b128 v[184:187], v228 offset:1024
	ds_read_b128 v[188:191], v228 offset:2048
	ds_read_b128 v[192:195], v228 offset:3072
	ds_read_b128 v[196:199], v228 offset:4096
	ds_read_b128 v[200:203], v228 offset:5120
	ds_read_b128 v[230:233], v228 offset:6144
	ds_read_b128 v[234:237], v228 offset:7168
	global_load_lds_dwordx4 v[212:213], off
	v_lshl_add_u64 v[212:213], s[26:27], 0, v[160:161]
	s_add_i32 m0, s73, 0xe000
	s_nop 0
	global_load_lds_dwordx4 v[212:213], off
	s_waitcnt vmcnt(8)
	s_waitcnt lgkmcnt(0)
	s_barrier
	s_setprio 1
	s_waitcnt lgkmcnt(0)
	v_mfma_f32_16x16x32_bf16 v[124:127], v[128:131], v[180:183], v[124:127]
	v_mfma_f32_16x16x32_bf16 v[120:123], v[136:139], v[180:183], v[120:123]
	v_mfma_f32_16x16x32_bf16 v[116:119], v[128:131], v[188:191], v[116:119]
	v_mfma_f32_16x16x32_bf16 v[112:115], v[136:139], v[188:191], v[112:115]
	v_mfma_f32_16x16x32_bf16 v[108:111], v[128:131], v[196:199], v[108:111]
	v_mfma_f32_16x16x32_bf16 v[104:107], v[136:139], v[196:199], v[104:107]
	v_mfma_f32_16x16x32_bf16 v[100:103], v[128:131], v[230:233], v[100:103]
	v_mfma_f32_16x16x32_bf16 v[96:99], v[136:139], v[230:233], v[96:99]
	v_mfma_f32_16x16x32_bf16 v[124:127], v[132:135], v[184:187], v[124:127]
	v_mfma_f32_16x16x32_bf16 v[120:123], v[140:143], v[184:187], v[120:123]
	v_mfma_f32_16x16x32_bf16 v[116:119], v[132:135], v[192:195], v[116:119]
	v_mfma_f32_16x16x32_bf16 v[112:115], v[140:143], v[192:195], v[112:115]
	v_mfma_f32_16x16x32_bf16 v[108:111], v[132:135], v[200:203], v[108:111]
	v_mfma_f32_16x16x32_bf16 v[104:107], v[140:143], v[200:203], v[104:107]
	v_mfma_f32_16x16x32_bf16 v[100:103], v[132:135], v[234:237], v[100:103]
	v_mfma_f32_16x16x32_bf16 v[96:99], v[140:143], v[234:237], v[96:99]
	v_mfma_f32_16x16x32_bf16 v[60:63], v[164:167], v[180:183], v[60:63]
	v_mfma_f32_16x16x32_bf16 v[56:59], v[172:175], v[180:183], v[56:59]
	v_mfma_f32_16x16x32_bf16 v[52:55], v[164:167], v[188:191], v[52:55]
	v_mfma_f32_16x16x32_bf16 v[48:51], v[172:175], v[188:191], v[48:51]
	v_mfma_f32_16x16x32_bf16 v[44:47], v[164:167], v[196:199], v[44:47]
	v_mfma_f32_16x16x32_bf16 v[40:43], v[172:175], v[196:199], v[40:43]
	v_mfma_f32_16x16x32_bf16 v[36:39], v[164:167], v[230:233], v[36:39]
	v_mfma_f32_16x16x32_bf16 v[32:35], v[172:175], v[230:233], v[32:35]
	v_mfma_f32_16x16x32_bf16 v[60:63], v[168:171], v[184:187], v[60:63]
	v_mfma_f32_16x16x32_bf16 v[56:59], v[176:179], v[184:187], v[56:59]
	v_mfma_f32_16x16x32_bf16 v[52:55], v[168:171], v[192:195], v[52:55]
	v_mfma_f32_16x16x32_bf16 v[48:51], v[176:179], v[192:195], v[48:51]
	v_mfma_f32_16x16x32_bf16 v[44:47], v[168:171], v[200:203], v[44:47]
	v_mfma_f32_16x16x32_bf16 v[40:43], v[176:179], v[200:203], v[40:43]
	v_mfma_f32_16x16x32_bf16 v[36:39], v[168:171], v[234:237], v[36:39]
	v_mfma_f32_16x16x32_bf16 v[32:35], v[176:179], v[234:237], v[32:35]
	s_setprio 0
	s_barrier
; #define PG8_STAGE(bufoff, gbase, voff) do { _Pragma("unroll") for (int _i = 0; _i < 2; ++_i) \
;     __builtin_amdgcn_global_load_lds((const unsigned*)((const char*)(gbase) + (voff)[_i]), (LAS unsigned*)(lds + (bufoff) + ldsw + _i * 8192), 16, 0, 0); } while (0)
; #define PG8_LDA(dst, b, h) do { _Pragma("unroll") for (int m = 0; m < 4; ++m) _Pragma("unroll") for (int k = 0; k < 2; ++k) dst[m][k] = *(const LAS bf16x8*)(lds + PG8_SA(b, h) + aoff + m * 2048 + k * 1024); } while (0)
; #define PG8_LDB(dst, b, h) do { _Pragma("unroll") for (int n = 0; n < 2; ++n) _Pragma("unroll") for (int k = 0; k < 2; ++k) dst[n][k] = *(const LAS bf16x8*)(lds + PG8_SB(b, h) + boff + n * 2048 + k * 1024); } while (0)
; #define PG8_MMA(ai, bj, At, Bt) do { __builtin_amdgcn_s_setprio(1); _Pragma("unroll") for (int m = 0; m < 4; ++m) _Pragma("unroll") for (int n = 0; n < 2; ++n) _Pragma("unroll") for (int k = 0; k < 2; ++k) \
;     acc[ai][bj][m][n] = __builtin_amdgcn_mfma_f32_16x16x32_bf16(Bt[n][k], At[m][k], acc[ai][bj][m][n], 0, 0, 0); __builtin_amdgcn_s_setprio(0); } while (0)
; #define PG8_WAIT_V(n) asm volatile("s_waitcnt vmcnt(" #n ")" ::: "memory")
; #define PG8_WAIT_L(n) asm volatile("s_waitcnt lgkmcnt(" #n ")" ::: "memory")
; #define PG8_BAR __builtin_amdgcn_s_barrier()
; #define PG8_SCHED __builtin_amdgcn_sched_barrier(0)
; DI void gemm_phase(const GemmDesc& g, LAS unsigned char* lds) {
;     ...
;       PG8_LDA(At, 0, 1); PG8_STAGE(PG8_SB(0, 0), b2, voffB); PG8_STAGE(PG8_SB(0, 1), b2 + hstep, voffB); PG8_STAGE(PG8_SA(0, 0), a2, voffA);
;       PG8_WAIT_V(8); PG8_WAIT_L(0); PG8_BAR; PG8_MMA(1, 0, At, B0); PG8_MMA(1, 1, At, B1); PG8_BAR; PG8_SCHED;
;       PG8_LDB(B0, 1, 0); PG8_LDB(B1, 1, 1); PG8_SCHED; PG8_LDA(At, 1, 0); PG8_STAGE(PG8_SA(0, 1), a2 + hstep, voffA);
;       PG8_WAIT_V(8); PG8_WAIT_L(0); PG8_BAR; PG8_MMA(0, 0, At, B0); PG8_MMA(0, 1, At, B1); PG8_BAR; PG8_SCHED;
	s_add_i32 s51, s51, s72
	v_lshl_add_u64 v[212:213], s[86:87], 0, v[152:153]
	s_mov_b32 m0, s51
	ds_read_b128 v[180:183], v228 offset:16384
	ds_read_b128 v[184:187], v228 offset:17408
	ds_read_b128 v[188:191], v228 offset:18432
	ds_read_b128 v[192:195], v228 offset:19456
	ds_read_b128 v[196:199], v228 offset:20480
	ds_read_b128 v[200:203], v228 offset:21504
	ds_read_b128 v[230:233], v228 offset:22528
	ds_read_b128 v[234:237], v228 offset:23552
	global_load_lds_dwordx4 v[212:213], off
	s_add_i32 m0, s51, 0x2000
	v_lshl_add_u64 v[238:239], s[86:87], 0, v[156:157]
	s_add_u32 s86, s86, s20
	s_addc_u32 s87, s87, s21
	s_add_i32 s49, s49, s72
	global_load_lds_dwordx4 v[238:239], off
	v_lshl_add_u64 v[240:241], s[86:87], 0, v[152:153]
	s_mov_b32 m0, s49
	v_lshl_add_u64 v[242:243], s[86:87], 0, v[156:157]
	global_load_lds_dwordx4 v[240:241], off
	s_add_i32 m0, s49, 0x2000
	v_lshl_add_u64 v[244:245], s[44:45], 0, v[150:151]
	global_load_lds_dwordx4 v[242:243], off
	s_mov_b32 m0, s73
	v_lshl_add_u64 v[246:247], s[44:45], 0, v[154:155]
	global_load_lds_dwordx4 v[244:245], off
	s_mov_b32 m0, s60
	s_nop 0
	global_load_lds_dwordx4 v[246:247], off
	s_waitcnt vmcnt(8)
	s_waitcnt lgkmcnt(0)
	s_barrier
	s_setprio 1
	s_waitcnt lgkmcnt(0)
	v_mfma_f32_16x16x32_bf16 v[92:95], v[128:131], v[180:183], v[92:95]
	v_mfma_f32_16x16x32_bf16 v[88:91], v[136:139], v[180:183], v[88:91]
	v_mfma_f32_16x16x32_bf16 v[84:87], v[128:131], v[188:191], v[84:87]
	v_mfma_f32_16x16x32_bf16 v[80:83], v[136:139], v[188:191], v[80:83]
	v_mfma_f32_16x16x32_bf16 v[76:79], v[128:131], v[196:199], v[76:79]
	v_mfma_f32_16x16x32_bf16 v[72:75], v[136:139], v[196:199], v[72:75]
	v_mfma_f32_16x16x32_bf16 v[68:71], v[128:131], v[230:233], v[68:71]
	v_mfma_f32_16x16x32_bf16 v[64:67], v[136:139], v[230:233], v[64:67]
	v_mfma_f32_16x16x32_bf16 v[92:95], v[132:135], v[184:187], v[92:95]
	v_mfma_f32_16x16x32_bf16 v[88:91], v[140:143], v[184:187], v[88:91]
	v_mfma_f32_16x16x32_bf16 v[84:87], v[132:135], v[192:195], v[84:87]
	v_mfma_f32_16x16x32_bf16 v[80:83], v[140:143], v[192:195], v[80:83]
	v_mfma_f32_16x16x32_bf16 v[76:79], v[132:135], v[200:203], v[76:79]
	v_mfma_f32_16x16x32_bf16 v[72:75], v[140:143], v[200:203], v[72:75]
	v_mfma_f32_16x16x32_bf16 v[68:71], v[132:135], v[234:237], v[68:71]
	v_mfma_f32_16x16x32_bf16 v[64:67], v[140:143], v[234:237], v[64:67]
	v_mfma_f32_16x16x32_bf16 v[28:31], v[164:167], v[180:183], v[28:31]
	v_mfma_f32_16x16x32_bf16 v[24:27], v[172:175], v[180:183], v[24:27]
	v_mfma_f32_16x16x32_bf16 v[20:23], v[164:167], v[188:191], v[20:23]
	v_mfma_f32_16x16x32_bf16 v[16:19], v[172:175], v[188:191], v[16:19]
	v_mfma_f32_16x16x32_bf16 v[12:15], v[164:167], v[196:199], v[12:15]
	v_mfma_f32_16x16x32_bf16 v[8:11], v[172:175], v[196:199], v[8:11]
	v_mfma_f32_16x16x32_bf16 v[4:7], v[164:167], v[230:233], v[4:7]
	v_mfma_f32_16x16x32_bf16 v[0:3], v[172:175], v[230:233], v[0:3]
	v_mfma_f32_16x16x32_bf16 v[28:31], v[168:171], v[184:187], v[28:31]
	v_mfma_f32_16x16x32_bf16 v[24:27], v[176:179], v[184:187], v[24:27]
	v_mfma_f32_16x16x32_bf16 v[20:23], v[168:171], v[192:195], v[20:23]
	v_mfma_f32_16x16x32_bf16 v[16:19], v[176:179], v[192:195], v[16:19]
	v_mfma_f32_16x16x32_bf16 v[12:15], v[168:171], v[200:203], v[12:15]
	v_mfma_f32_16x16x32_bf16 v[8:11], v[176:179], v[200:203], v[8:11]
	v_mfma_f32_16x16x32_bf16 v[4:7], v[168:171], v[234:237], v[4:7]
	v_mfma_f32_16x16x32_bf16 v[0:3], v[176:179], v[234:237], v[0:3]
	s_setprio 0
	s_barrier
	s_add_i32 s49, 0, 0x18000
	s_add_i32 s51, 0, 0x1c000
	v_add_u32_e32 v140, s49, v219
	v_add_u32_e32 v148, s51, v219
	ds_read_b128 v[128:131], v140
	ds_read_b128 v[132:135], v140 offset:1024
	ds_read_b128 v[136:139], v140 offset:2048
	ds_read_b128 v[140:143], v140 offset:3072
	ds_read_b128 v[164:167], v148
	ds_read_b128 v[168:171], v148 offset:1024
	ds_read_b128 v[172:175], v148 offset:2048
	ds_read_b128 v[176:179], v148 offset:3072
	s_add_u32 s44, s44, s20
	s_addc_u32 s45, s45, s21
	s_mov_b32 m0, s61
	v_lshl_add_u64 v[248:249], s[44:45], 0, v[150:151]
	ds_read_b128 v[180:183], v228 offset:32768
	ds_read_b128 v[184:187], v228 offset:33792
	ds_read_b128 v[188:191], v228 offset:34816
	ds_read_b128 v[192:195], v228 offset:35840
	ds_read_b128 v[196:199], v228 offset:36864
	ds_read_b128 v[200:203], v228 offset:37888
	ds_read_b128 v[230:233], v228 offset:38912
	ds_read_b128 v[234:237], v228 offset:39936
	global_load_lds_dwordx4 v[248:249], off
	v_lshl_add_u64 v[248:249], s[44:45], 0, v[154:155]
	s_mov_b32 m0, s93
	s_nop 0
	global_load_lds_dwordx4 v[248:249], off
	s_waitcnt vmcnt(8)
	s_waitcnt lgkmcnt(0)
	s_barrier
; #define PG8_STAGE(bufoff, gbase, voff) do { _Pragma("unroll") for (int _i = 0; _i < 2; ++_i) \
;     __builtin_amdgcn_global_load_lds((const unsigned*)((const char*)(gbase) + (voff)[_i]), (LAS unsigned*)(lds + (bufoff) + ldsw + _i * 8192), 16, 0, 0); } while (0)
; #define PG8_LDA(dst, b, h) do { _Pragma("unroll") for (int m = 0; m < 4; ++m) _Pragma("unroll") for (int k = 0; k < 2; ++k) dst[m][k] = *(const LAS bf16x8*)(lds + PG8_SA(b, h) + aoff + m * 2048 + k * 1024); } while (0)
; #define PG8_MMA(ai, bj, At, Bt) do { __builtin_amdgcn_s_setprio(1); _Pragma("unroll") for (int m = 0; m < 4; ++m) _Pragma("unroll") for (int n = 0; n < 2; ++n) _Pragma("unroll") for (int k = 0; k < 2; ++k) \
;     acc[ai][bj][m][n] = __builtin_amdgcn_mfma_f32_16x16x32_bf16(Bt[n][k], At[m][k], acc[ai][bj][m][n], 0, 0, 0); __builtin_amdgcn_s_setprio(0); } while (0)
; #define PG8_WAIT_V(n) asm volatile("s_waitcnt vmcnt(" #n ")" ::: "memory")
; #define PG8_WAIT_L(n) asm volatile("s_waitcnt lgkmcnt(" #n ")" ::: "memory")
; #define PG8_BAR __builtin_amdgcn_s_barrier()
; #define PG8_SCHED __builtin_amdgcn_sched_barrier(0)
; DI void gemm_phase(const GemmDesc& g, LAS unsigned char* lds) {
;     ...
;       PG8_WAIT_V(8); PG8_WAIT_L(0); PG8_BAR; PG8_MMA(0, 0, At, B0); PG8_MMA(0, 1, At, B1); PG8_BAR; PG8_SCHED;
;       PG8_LDA(At, 1, 1); PG8_STAGE(PG8_SB(1, 0), b3, voffB); PG8_STAGE(PG8_SB(1, 1), b3 + hstep, voffB); PG8_STAGE(PG8_SA(1, 0), a3, voffA);
;       PG8_WAIT_V(8); PG8_WAIT_L(0); PG8_BAR; PG8_MMA(1, 0, At, B0); PG8_MMA(1, 1, At, B1); PG8_BAR; PG8_SCHED;
;     }
;     if (wr == 0) PG8_BAR;
	s_setprio 1
	s_waitcnt lgkmcnt(0)
	v_mfma_f32_16x16x32_bf16 v[124:127], v[128:131], v[180:183], v[124:127]
	v_mfma_f32_16x16x32_bf16 v[120:123], v[136:139], v[180:183], v[120:123]
	v_mfma_f32_16x16x32_bf16 v[116:119], v[128:131], v[188:191], v[116:119]
	v_mfma_f32_16x16x32_bf16 v[112:115], v[136:139], v[188:191], v[112:115]
	v_mfma_f32_16x16x32_bf16 v[108:111], v[128:131], v[196:199], v[108:111]
	v_mfma_f32_16x16x32_bf16 v[104:107], v[136:139], v[196:199], v[104:107]
	v_mfma_f32_16x16x32_bf16 v[100:103], v[128:131], v[230:233], v[100:103]
	v_mfma_f32_16x16x32_bf16 v[96:99], v[136:139], v[230:233], v[96:99]
	v_mfma_f32_16x16x32_bf16 v[124:127], v[132:135], v[184:187], v[124:127]
	v_mfma_f32_16x16x32_bf16 v[120:123], v[140:143], v[184:187], v[120:123]
	v_mfma_f32_16x16x32_bf16 v[116:119], v[132:135], v[192:195], v[116:119]
	v_mfma_f32_16x16x32_bf16 v[112:115], v[140:143], v[192:195], v[112:115]
	v_mfma_f32_16x16x32_bf16 v[108:111], v[132:135], v[200:203], v[108:111]
	v_mfma_f32_16x16x32_bf16 v[104:107], v[140:143], v[200:203], v[104:107]
	v_mfma_f32_16x16x32_bf16 v[100:103], v[132:135], v[234:237], v[100:103]
	v_mfma_f32_16x16x32_bf16 v[96:99], v[140:143], v[234:237], v[96:99]
	v_mfma_f32_16x16x32_bf16 v[60:63], v[164:167], v[180:183], v[60:63]
	v_mfma_f32_16x16x32_bf16 v[56:59], v[172:175], v[180:183], v[56:59]
	v_mfma_f32_16x16x32_bf16 v[52:55], v[164:167], v[188:191], v[52:55]
	v_mfma_f32_16x16x32_bf16 v[48:51], v[172:175], v[188:191], v[48:51]
	v_mfma_f32_16x16x32_bf16 v[44:47], v[164:167], v[196:199], v[44:47]
	v_mfma_f32_16x16x32_bf16 v[40:43], v[172:175], v[196:199], v[40:43]
	v_mfma_f32_16x16x32_bf16 v[36:39], v[164:167], v[230:233], v[36:39]
	v_mfma_f32_16x16x32_bf16 v[32:35], v[172:175], v[230:233], v[32:35]
	v_mfma_f32_16x16x32_bf16 v[60:63], v[168:171], v[184:187], v[60:63]
	v_mfma_f32_16x16x32_bf16 v[56:59], v[176:179], v[184:187], v[56:59]
	v_mfma_f32_16x16x32_bf16 v[52:55], v[168:171], v[192:195], v[52:55]
	v_mfma_f32_16x16x32_bf16 v[48:51], v[176:179], v[192:195], v[48:51]
	v_mfma_f32_16x16x32_bf16 v[44:47], v[168:171], v[200:203], v[44:47]
	v_mfma_f32_16x16x32_bf16 v[40:43], v[176:179], v[200:203], v[40:43]
	v_mfma_f32_16x16x32_bf16 v[36:39], v[168:171], v[234:237], v[36:39]
	v_mfma_f32_16x16x32_bf16 v[32:35], v[176:179], v[234:237], v[32:35]
	s_setprio 0
	s_barrier
	s_add_i32 s44, s49, s72
	v_lshl_add_u64 v[212:213], v[212:213], 0, s[28:29]
	s_mov_b32 m0, s44
	ds_read_b128 v[180:183], v228 offset:49152
	ds_read_b128 v[184:187], v228 offset:50176
	ds_read_b128 v[188:191], v228 offset:51200
	ds_read_b128 v[192:195], v228 offset:52224
	ds_read_b128 v[196:199], v228 offset:53248
	ds_read_b128 v[200:203], v228 offset:54272
	ds_read_b128 v[230:233], v228 offset:55296
	ds_read_b128 v[234:237], v228 offset:56320
	global_load_lds_dwordx4 v[212:213], off
	v_lshl_add_u64 v[212:213], v[238:239], 0, s[28:29]
	s_add_i32 m0, s44, 0x2000
	s_add_i32 s44, s51, s72
	global_load_lds_dwordx4 v[212:213], off
	v_lshl_add_u64 v[212:213], v[240:241], 0, s[28:29]
	s_mov_b32 m0, s44
	s_nop 0
	global_load_lds_dwordx4 v[212:213], off
	v_lshl_add_u64 v[212:213], v[242:243], 0, s[28:29]
	s_add_i32 m0, s44, 0x2000
	s_nop 0
	global_load_lds_dwordx4 v[212:213], off
	v_lshl_add_u64 v[212:213], v[244:245], 0, s[28:29]
	s_mov_b32 m0, s95
	s_nop 0
	global_load_lds_dwordx4 v[212:213], off
	v_lshl_add_u64 v[212:213], v[246:247], 0, s[28:29]
	s_mov_b32 m0, s96
	s_nop 0
	global_load_lds_dwordx4 v[212:213], off
	s_waitcnt vmcnt(8)
	s_waitcnt lgkmcnt(0)
	s_barrier
	s_setprio 1
	s_waitcnt lgkmcnt(0)
	v_mfma_f32_16x16x32_bf16 v[92:95], v[128:131], v[180:183], v[92:95]
	v_mfma_f32_16x16x32_bf16 v[88:91], v[136:139], v[180:183], v[88:91]
	v_mfma_f32_16x16x32_bf16 v[84:87], v[128:131], v[188:191], v[84:87]
	v_mfma_f32_16x16x32_bf16 v[80:83], v[136:139], v[188:191], v[80:83]
	v_mfma_f32_16x16x32_bf16 v[76:79], v[128:131], v[196:199], v[76:79]
	v_mfma_f32_16x16x32_bf16 v[72:75], v[136:139], v[196:199], v[72:75]
	v_mfma_f32_16x16x32_bf16 v[68:71], v[128:131], v[230:233], v[68:71]
	v_mfma_f32_16x16x32_bf16 v[64:67], v[136:139], v[230:233], v[64:67]
	v_mfma_f32_16x16x32_bf16 v[92:95], v[132:135], v[184:187], v[92:95]
	v_mfma_f32_16x16x32_bf16 v[88:91], v[140:143], v[184:187], v[88:91]
	v_mfma_f32_16x16x32_bf16 v[84:87], v[132:135], v[192:195], v[84:87]
	v_mfma_f32_16x16x32_bf16 v[80:83], v[140:143], v[192:195], v[80:83]
	v_mfma_f32_16x16x32_bf16 v[76:79], v[132:135], v[200:203], v[76:79]
	v_mfma_f32_16x16x32_bf16 v[72:75], v[140:143], v[200:203], v[72:75]
	v_mfma_f32_16x16x32_bf16 v[68:71], v[132:135], v[234:237], v[68:71]
	v_mfma_f32_16x16x32_bf16 v[64:67], v[140:143], v[234:237], v[64:67]
	v_mfma_f32_16x16x32_bf16 v[28:31], v[164:167], v[180:183], v[28:31]
	v_mfma_f32_16x16x32_bf16 v[24:27], v[172:175], v[180:183], v[24:27]
	v_mfma_f32_16x16x32_bf16 v[20:23], v[164:167], v[188:191], v[20:23]
	v_mfma_f32_16x16x32_bf16 v[16:19], v[172:175], v[188:191], v[16:19]
	v_mfma_f32_16x16x32_bf16 v[12:15], v[164:167], v[196:199], v[12:15]
	v_mfma_f32_16x16x32_bf16 v[8:11], v[172:175], v[196:199], v[8:11]
	v_mfma_f32_16x16x32_bf16 v[4:7], v[164:167], v[230:233], v[4:7]
	v_mfma_f32_16x16x32_bf16 v[0:3], v[172:175], v[230:233], v[0:3]
	v_mfma_f32_16x16x32_bf16 v[28:31], v[168:171], v[184:187], v[28:31]
	v_mfma_f32_16x16x32_bf16 v[24:27], v[176:179], v[184:187], v[24:27]
	v_mfma_f32_16x16x32_bf16 v[20:23], v[168:171], v[192:195], v[20:23]
	v_mfma_f32_16x16x32_bf16 v[16:19], v[176:179], v[192:195], v[16:19]
	v_mfma_f32_16x16x32_bf16 v[12:15], v[168:171], v[200:203], v[12:15]
	v_mfma_f32_16x16x32_bf16 v[8:11], v[176:179], v[200:203], v[8:11]
	v_mfma_f32_16x16x32_bf16 v[4:7], v[168:171], v[234:237], v[4:7]
	v_mfma_f32_16x16x32_bf16 v[0:3], v[176:179], v[234:237], v[0:3]
	s_setprio 0
	s_barrier
	s_add_u32 s46, s46, 0x100
	s_addc_u32 s47, s47, 0
	s_add_u32 s26, s26, 0x100
	s_addc_u32 s27, s27, 0
	s_cmp_ge_u32 s48, s82
	s_mov_b32 s44, s48
	s_cbranch_scc0 .LBB0_132
	s_and_b64 vcc, exec, s[56:57]
	s_cbranch_vccz .LBB0_135
	s_barrier

; DI unsigned pk(float lo, float hi) { f32x2 v = {lo, hi}; bf2_t b = __builtin_convertvector(v, bf2_t); return __builtin_bit_cast(unsigned, b); }
; DI void gemm_epilogue(const GemmDesc& g, f32x4 (&acc)[2][2][4][2], int brow, int bcol, int wr, int wc, int fr, int fq) {
;     ...
;           const int row = rowb + ai * HALF + m * 16;
;           f32x4 v0 = acc[ai][bj][m][0], v1 = acc[ai][bj][m][1];
;           if (g.rowscale) { const float ru = gld<float>(g.rowscale + row); v0 = v0 * ru; v1 = v1 * ru; }
;           v0 = v0 + b0; v1 = v1 + b1;
;           if (epi == EPI_RELU2) {
; #pragma unroll
;             for (int j = 0; j < 4; ++j) { float r0 = fmaxf(v0[j], 0.f), r1 = fmaxf(v1[j], 0.f); v0[j] = r0 * r0; v1[j] = r1 * r1; }
;           }
;           u32x4 w; w.x = pk(v0[0], v0[1]); w.y = pk(v0[2], v0[3]); w.z = pk(v1[0], v1[1]); w.w = pk(v1[2], v1[3]);
.LBB0_153:
	v_cndmask_b32_e64 v138, 0, 1, s[40:41]
	s_waitcnt vmcnt(0)
	v_pk_add_f32 v[126:127], v[134:135], v[126:127]
	v_pk_add_f32 v[124:125], v[132:133], v[124:125]
	v_pk_add_f32 v[122:123], v[130:131], v[122:123]
	v_cmp_ne_u32_e64 s[46:47], 1, v138
	s_andn2_b64 vcc, exec, s[40:41]
	v_pk_add_f32 v[120:121], v[128:129], v[120:121]
	s_cbranch_vccnz .LBB0_155
	v_max_f32_e32 v124, 0, v124
	v_max_f32_e32 v120, 0, v120
	v_max_f32_e32 v125, 0, v125
	v_max_f32_e32 v121, 0, v121
	v_max_f32_e32 v126, 0, v126
	v_max_f32_e32 v122, 0, v122
	v_max_f32_e32 v127, 0, v127
	v_max_f32_e32 v123, 0, v123
	v_pk_mul_f32 v[124:125], v[124:125], v[124:125]
	v_pk_mul_f32 v[126:127], v[126:127], v[126:127]
	v_pk_mul_f32 v[120:121], v[120:121], v[120:121]
	v_pk_mul_f32 v[122:123], v[122:123], v[122:123]

; DI unsigned pk(float lo, float hi) { f32x2 v = {lo, hi}; bf2_t b = __builtin_convertvector(v, bf2_t); return __builtin_bit_cast(unsigned, b); }
; DI void gemm_epilogue(const GemmDesc& g, f32x4 (&acc)[2][2][4][2], int brow, int bcol, int wr, int wc, int fr, int fq) {
;     ...
;           const int row = rowb + ai * HALF + m * 16;
;           f32x4 v0 = acc[ai][bj][m][0], v1 = acc[ai][bj][m][1];
;           if (g.rowscale) { const float ru = gld<float>(g.rowscale + row); v0 = v0 * ru; v1 = v1 * ru; }
;           v0 = v0 + b0; v1 = v1 + b1;
;           if (epi == EPI_RELU2) {
; #pragma unroll
;             for (int j = 0; j < 4; ++j) { float r0 = fmaxf(v0[j], 0.f), r1 = fmaxf(v1[j], 0.f); v0[j] = r0 * r0; v1[j] = r1 * r1; }
;           }
;           u32x4 w; w.x = pk(v0[0], v0[1]); w.y = pk(v0[2], v0[3]); w.z = pk(v1[0], v1[1]); w.w = pk(v1[2], v1[3]);
.LBB0_157:
	v_pk_add_f32 v[118:119], v[134:135], v[118:119]
	v_pk_add_f32 v[116:117], v[132:133], v[116:117]
	v_pk_add_f32 v[114:115], v[130:131], v[114:115]
	s_and_b64 vcc, exec, s[46:47]
	v_pk_add_f32 v[112:113], v[128:129], v[112:113]
	s_cbranch_vccnz .LBB0_159
	v_max_f32_e32 v116, 0, v116
	v_max_f32_e32 v112, 0, v112
	v_max_f32_e32 v117, 0, v117
	v_max_f32_e32 v113, 0, v113
	v_max_f32_e32 v118, 0, v118
	v_max_f32_e32 v114, 0, v114
	v_max_f32_e32 v119, 0, v119
	v_max_f32_e32 v115, 0, v115
	v_pk_mul_f32 v[116:117], v[116:117], v[116:117]
	v_pk_mul_f32 v[118:119], v[118:119], v[118:119]
	v_pk_mul_f32 v[112:113], v[112:113], v[112:113]
	v_pk_mul_f32 v[114:115], v[114:115], v[114:115]

; DI unsigned pk(float lo, float hi) { f32x2 v = {lo, hi}; bf2_t b = __builtin_convertvector(v, bf2_t); return __builtin_bit_cast(unsigned, b); }
; DI void gemm_epilogue(const GemmDesc& g, f32x4 (&acc)[2][2][4][2], int brow, int bcol, int wr, int wc, int fr, int fq) {
;     ...
;           const int row = rowb + ai * HALF + m * 16;
;           f32x4 v0 = acc[ai][bj][m][0], v1 = acc[ai][bj][m][1];
;           if (g.rowscale) { const float ru = gld<float>(g.rowscale + row); v0 = v0 * ru; v1 = v1 * ru; }
;           v0 = v0 + b0; v1 = v1 + b1;
;           if (epi == EPI_RELU2) {
; #pragma unroll
;             for (int j = 0; j < 4; ++j) { float r0 = fmaxf(v0[j], 0.f), r1 = fmaxf(v1[j], 0.f); v0[j] = r0 * r0; v1[j] = r1 * r1; }
;           }
;           u32x4 w; w.x = pk(v0[0], v0[1]); w.y = pk(v0[2], v0[3]); w.z = pk(v1[0], v1[1]); w.w = pk(v1[2], v1[3]);
.LBB0_161:
	v_pk_add_f32 v[110:111], v[134:135], v[110:111]
	v_pk_add_f32 v[108:109], v[132:133], v[108:109]
	v_pk_add_f32 v[106:107], v[130:131], v[106:107]
	s_and_b64 vcc, exec, s[46:47]
	v_pk_add_f32 v[104:105], v[128:129], v[104:105]
	s_cbranch_vccnz .LBB0_163
	v_max_f32_e32 v108, 0, v108
	v_max_f32_e32 v104, 0, v104
	v_max_f32_e32 v109, 0, v109
	v_max_f32_e32 v105, 0, v105
	v_max_f32_e32 v110, 0, v110
	v_max_f32_e32 v106, 0, v106
	v_max_f32_e32 v111, 0, v111
	v_max_f32_e32 v107, 0, v107
	v_pk_mul_f32 v[108:109], v[108:109], v[108:109]
	v_pk_mul_f32 v[110:111], v[110:111], v[110:111]
	v_pk_mul_f32 v[104:105], v[104:105], v[104:105]
	v_pk_mul_f32 v[106:107], v[106:107], v[106:107]

; DI unsigned pk(float lo, float hi) { f32x2 v = {lo, hi}; bf2_t b = __builtin_convertvector(v, bf2_t); return __builtin_bit_cast(unsigned, b); }
; DI void gemm_epilogue(const GemmDesc& g, f32x4 (&acc)[2][2][4][2], int brow, int bcol, int wr, int wc, int fr, int fq) {
;     ...
;           const int row = rowb + ai * HALF + m * 16;
;           f32x4 v0 = acc[ai][bj][m][0], v1 = acc[ai][bj][m][1];
;           if (g.rowscale) { const float ru = gld<float>(g.rowscale + row); v0 = v0 * ru; v1 = v1 * ru; }
;           v0 = v0 + b0; v1 = v1 + b1;
;           if (epi == EPI_RELU2) {
; #pragma unroll
;             for (int j = 0; j < 4; ++j) { float r0 = fmaxf(v0[j], 0.f), r1 = fmaxf(v1[j], 0.f); v0[j] = r0 * r0; v1[j] = r1 * r1; }
;           }
;           u32x4 w; w.x = pk(v0[0], v0[1]); w.y = pk(v0[2], v0[3]); w.z = pk(v1[0], v1[1]); w.w = pk(v1[2], v1[3]);
.LBB0_165:
	v_pk_add_f32 v[102:103], v[134:135], v[102:103]
	v_pk_add_f32 v[100:101], v[132:133], v[100:101]
	v_pk_add_f32 v[98:99], v[130:131], v[98:99]
	s_and_b64 vcc, exec, s[46:47]
	v_pk_add_f32 v[96:97], v[128:129], v[96:97]
	s_cbranch_vccnz .LBB0_167
	v_max_f32_e32 v100, 0, v100
	v_max_f32_e32 v96, 0, v96
	v_max_f32_e32 v101, 0, v101
	v_max_f32_e32 v97, 0, v97
	v_max_f32_e32 v102, 0, v102
	v_max_f32_e32 v98, 0, v98
	v_max_f32_e32 v103, 0, v103
	v_max_f32_e32 v99, 0, v99
	v_pk_mul_f32 v[100:101], v[100:101], v[100:101]
	v_pk_mul_f32 v[102:103], v[102:103], v[102:103]
	v_pk_mul_f32 v[96:97], v[96:97], v[96:97]
	v_pk_mul_f32 v[98:99], v[98:99], v[98:99]

; DI unsigned pk(float lo, float hi) { f32x2 v = {lo, hi}; bf2_t b = __builtin_convertvector(v, bf2_t); return __builtin_bit_cast(unsigned, b); }
; DI void gemm_epilogue(const GemmDesc& g, f32x4 (&acc)[2][2][4][2], int brow, int bcol, int wr, int wc, int fr, int fq) {
;     ...
;           const int row = rowb + ai * HALF + m * 16;
;           f32x4 v0 = acc[ai][bj][m][0], v1 = acc[ai][bj][m][1];
;           if (g.rowscale) { const float ru = gld<float>(g.rowscale + row); v0 = v0 * ru; v1 = v1 * ru; }
;           v0 = v0 + b0; v1 = v1 + b1;
;           if (epi == EPI_RELU2) {
; #pragma unroll
;             for (int j = 0; j < 4; ++j) { float r0 = fmaxf(v0[j], 0.f), r1 = fmaxf(v1[j], 0.f); v0[j] = r0 * r0; v1[j] = r1 * r1; }
;           }
;           u32x4 w; w.x = pk(v0[0], v0[1]); w.y = pk(v0[2], v0[3]); w.z = pk(v1[0], v1[1]); w.w = pk(v1[2], v1[3]);
.LBB0_169:
	v_pk_add_f32 v[94:95], v[134:135], v[94:95]
	v_pk_add_f32 v[92:93], v[132:133], v[92:93]
	v_pk_add_f32 v[90:91], v[130:131], v[90:91]
	s_and_b64 vcc, exec, s[46:47]
	v_pk_add_f32 v[88:89], v[128:129], v[88:89]
	s_cbranch_vccnz .LBB0_171
	v_max_f32_e32 v92, 0, v92
	v_max_f32_e32 v88, 0, v88
	v_max_f32_e32 v93, 0, v93
	v_max_f32_e32 v89, 0, v89
	v_max_f32_e32 v94, 0, v94
	v_max_f32_e32 v90, 0, v90
	v_max_f32_e32 v95, 0, v95
	v_max_f32_e32 v91, 0, v91
	v_pk_mul_f32 v[92:93], v[92:93], v[92:93]
	v_pk_mul_f32 v[94:95], v[94:95], v[94:95]
	v_pk_mul_f32 v[88:89], v[88:89], v[88:89]
	v_pk_mul_f32 v[90:91], v[90:91], v[90:91]

; DI unsigned pk(float lo, float hi) { f32x2 v = {lo, hi}; bf2_t b = __builtin_convertvector(v, bf2_t); return __builtin_bit_cast(unsigned, b); }
; DI void gemm_epilogue(const GemmDesc& g, f32x4 (&acc)[2][2][4][2], int brow, int bcol, int wr, int wc, int fr, int fq) {
;     ...
;           const int row = rowb + ai * HALF + m * 16;
;           f32x4 v0 = acc[ai][bj][m][0], v1 = acc[ai][bj][m][1];
;           if (g.rowscale) { const float ru = gld<float>(g.rowscale + row); v0 = v0 * ru; v1 = v1 * ru; }
;           v0 = v0 + b0; v1 = v1 + b1;
;           if (epi == EPI_RELU2) {
; #pragma unroll
;             for (int j = 0; j < 4; ++j) { float r0 = fmaxf(v0[j], 0.f), r1 = fmaxf(v1[j], 0.f); v0[j] = r0 * r0; v1[j] = r1 * r1; }
;           }
;           u32x4 w; w.x = pk(v0[0], v0[1]); w.y = pk(v0[2], v0[3]); w.z = pk(v1[0], v1[1]); w.w = pk(v1[2], v1[3]);
.LBB0_173:
	v_pk_add_f32 v[86:87], v[134:135], v[86:87]
	v_pk_add_f32 v[84:85], v[132:133], v[84:85]
	v_pk_add_f32 v[82:83], v[130:131], v[82:83]
	s_and_b64 vcc, exec, s[46:47]
	v_pk_add_f32 v[80:81], v[128:129], v[80:81]
	s_cbranch_vccnz .LBB0_175
	v_max_f32_e32 v84, 0, v84
	v_max_f32_e32 v80, 0, v80
	v_max_f32_e32 v85, 0, v85
	v_max_f32_e32 v81, 0, v81
	v_max_f32_e32 v86, 0, v86
	v_max_f32_e32 v82, 0, v82
	v_max_f32_e32 v87, 0, v87
	v_max_f32_e32 v83, 0, v83
	v_pk_mul_f32 v[84:85], v[84:85], v[84:85]
	v_pk_mul_f32 v[86:87], v[86:87], v[86:87]
	v_pk_mul_f32 v[80:81], v[80:81], v[80:81]
	v_pk_mul_f32 v[82:83], v[82:83], v[82:83]

; DI unsigned pk(float lo, float hi) { f32x2 v = {lo, hi}; bf2_t b = __builtin_convertvector(v, bf2_t); return __builtin_bit_cast(unsigned, b); }
; DI void gemm_epilogue(const GemmDesc& g, f32x4 (&acc)[2][2][4][2], int brow, int bcol, int wr, int wc, int fr, int fq) {
;     ...
;           const int row = rowb + ai * HALF + m * 16;
;           f32x4 v0 = acc[ai][bj][m][0], v1 = acc[ai][bj][m][1];
;           if (g.rowscale) { const float ru = gld<float>(g.rowscale + row); v0 = v0 * ru; v1 = v1 * ru; }
;           v0 = v0 + b0; v1 = v1 + b1;
;           if (epi == EPI_RELU2) {
; #pragma unroll
;             for (int j = 0; j < 4; ++j) { float r0 = fmaxf(v0[j], 0.f), r1 = fmaxf(v1[j], 0.f); v0[j] = r0 * r0; v1[j] = r1 * r1; }
;           }
;           u32x4 w; w.x = pk(v0[0], v0[1]); w.y = pk(v0[2], v0[3]); w.z = pk(v1[0], v1[1]); w.w = pk(v1[2], v1[3]);
.LBB0_177:
	v_pk_add_f32 v[78:79], v[134:135], v[78:79]
	v_pk_add_f32 v[76:77], v[132:133], v[76:77]
	v_pk_add_f32 v[74:75], v[130:131], v[74:75]
	s_and_b64 vcc, exec, s[46:47]
	v_pk_add_f32 v[72:73], v[128:129], v[72:73]
	s_cbranch_vccnz .LBB0_179
	v_max_f32_e32 v76, 0, v76
	v_max_f32_e32 v72, 0, v72
	v_max_f32_e32 v77, 0, v77
	v_max_f32_e32 v73, 0, v73
	v_max_f32_e32 v78, 0, v78
	v_max_f32_e32 v74, 0, v74
	v_max_f32_e32 v79, 0, v79
	v_max_f32_e32 v75, 0, v75
	v_pk_mul_f32 v[76:77], v[76:77], v[76:77]
	v_pk_mul_f32 v[78:79], v[78:79], v[78:79]
	v_pk_mul_f32 v[72:73], v[72:73], v[72:73]
	v_pk_mul_f32 v[74:75], v[74:75], v[74:75]

; DI unsigned pk(float lo, float hi) { f32x2 v = {lo, hi}; bf2_t b = __builtin_convertvector(v, bf2_t); return __builtin_bit_cast(unsigned, b); }
; DI void gemm_epilogue(const GemmDesc& g, f32x4 (&acc)[2][2][4][2], int brow, int bcol, int wr, int wc, int fr, int fq) {
;     ...
;           const int row = rowb + ai * HALF + m * 16;
;           f32x4 v0 = acc[ai][bj][m][0], v1 = acc[ai][bj][m][1];
;           if (g.rowscale) { const float ru = gld<float>(g.rowscale + row); v0 = v0 * ru; v1 = v1 * ru; }
;           v0 = v0 + b0; v1 = v1 + b1;
;           if (epi == EPI_RELU2) {
; #pragma unroll
;             for (int j = 0; j < 4; ++j) { float r0 = fmaxf(v0[j], 0.f), r1 = fmaxf(v1[j], 0.f); v0[j] = r0 * r0; v1[j] = r1 * r1; }
;           }
;           u32x4 w; w.x = pk(v0[0], v0[1]); w.y = pk(v0[2], v0[3]); w.z = pk(v1[0], v1[1]); w.w = pk(v1[2], v1[3]);
.LBB0_181:
	v_pk_add_f32 v[70:71], v[134:135], v[70:71]
	v_pk_add_f32 v[68:69], v[132:133], v[68:69]
	v_pk_add_f32 v[66:67], v[130:131], v[66:67]
	s_and_b64 vcc, exec, s[46:47]
	v_pk_add_f32 v[64:65], v[128:129], v[64:65]
	s_cbranch_vccnz .LBB0_183
	v_max_f32_e32 v68, 0, v68
	v_max_f32_e32 v64, 0, v64
	v_max_f32_e32 v69, 0, v69
	v_max_f32_e32 v65, 0, v65
	v_max_f32_e32 v70, 0, v70
	v_max_f32_e32 v66, 0, v66
	v_max_f32_e32 v71, 0, v71
	v_max_f32_e32 v67, 0, v67
	v_pk_mul_f32 v[68:69], v[68:69], v[68:69]
	v_pk_mul_f32 v[70:71], v[70:71], v[70:71]
	v_pk_mul_f32 v[64:65], v[64:65], v[64:65]
	v_pk_mul_f32 v[66:67], v[66:67], v[66:67]

; DI unsigned pk(float lo, float hi) { f32x2 v = {lo, hi}; bf2_t b = __builtin_convertvector(v, bf2_t); return __builtin_bit_cast(unsigned, b); }
; DI void gemm_epilogue(const GemmDesc& g, f32x4 (&acc)[2][2][4][2], int brow, int bcol, int wr, int wc, int fr, int fq) {
;     ...
;           const int row = rowb + ai * HALF + m * 16;
;           f32x4 v0 = acc[ai][bj][m][0], v1 = acc[ai][bj][m][1];
;           if (g.rowscale) { const float ru = gld<float>(g.rowscale + row); v0 = v0 * ru; v1 = v1 * ru; }
;           v0 = v0 + b0; v1 = v1 + b1;
;           if (epi == EPI_RELU2) {
; #pragma unroll
;             for (int j = 0; j < 4; ++j) { float r0 = fmaxf(v0[j], 0.f), r1 = fmaxf(v1[j], 0.f); v0[j] = r0 * r0; v1[j] = r1 * r1; }
;           }
;           u32x4 w; w.x = pk(v0[0], v0[1]); w.y = pk(v0[2], v0[3]); w.z = pk(v1[0], v1[1]); w.w = pk(v1[2], v1[3]);
.LBB0_186:
	s_waitcnt vmcnt(0)
	v_pk_add_f32 v[62:63], v[70:71], v[62:63]
	v_pk_add_f32 v[60:61], v[68:69], v[60:61]
	v_pk_add_f32 v[58:59], v[66:67], v[58:59]
	s_and_b64 vcc, exec, s[46:47]
	v_pk_add_f32 v[56:57], v[64:65], v[56:57]
	s_cbranch_vccnz .LBB0_188
	v_max_f32_e32 v60, 0, v60
	v_max_f32_e32 v56, 0, v56
	v_max_f32_e32 v61, 0, v61
	v_max_f32_e32 v57, 0, v57
	v_max_f32_e32 v62, 0, v62
	v_max_f32_e32 v58, 0, v58
	v_max_f32_e32 v63, 0, v63
	v_max_f32_e32 v59, 0, v59
	v_pk_mul_f32 v[60:61], v[60:61], v[60:61]
	v_pk_mul_f32 v[62:63], v[62:63], v[62:63]
	v_pk_mul_f32 v[56:57], v[56:57], v[56:57]
	v_pk_mul_f32 v[58:59], v[58:59], v[58:59]

; DI unsigned pk(float lo, float hi) { f32x2 v = {lo, hi}; bf2_t b = __builtin_convertvector(v, bf2_t); return __builtin_bit_cast(unsigned, b); }
; DI void gemm_epilogue(const GemmDesc& g, f32x4 (&acc)[2][2][4][2], int brow, int bcol, int wr, int wc, int fr, int fq) {
;     ...
;           const int row = rowb + ai * HALF + m * 16;
;           f32x4 v0 = acc[ai][bj][m][0], v1 = acc[ai][bj][m][1];
;           if (g.rowscale) { const float ru = gld<float>(g.rowscale + row); v0 = v0 * ru; v1 = v1 * ru; }
;           v0 = v0 + b0; v1 = v1 + b1;
;           if (epi == EPI_RELU2) {
; #pragma unroll
;             for (int j = 0; j < 4; ++j) { float r0 = fmaxf(v0[j], 0.f), r1 = fmaxf(v1[j], 0.f); v0[j] = r0 * r0; v1[j] = r1 * r1; }
;           }
;           u32x4 w; w.x = pk(v0[0], v0[1]); w.y = pk(v0[2], v0[3]); w.z = pk(v1[0], v1[1]); w.w = pk(v1[2], v1[3]);
.LBB0_190:
	v_pk_add_f32 v[54:55], v[70:71], v[54:55]
	v_pk_add_f32 v[52:53], v[68:69], v[52:53]
	v_pk_add_f32 v[50:51], v[66:67], v[50:51]
	s_and_b64 vcc, exec, s[46:47]
	v_pk_add_f32 v[48:49], v[64:65], v[48:49]
	s_cbranch_vccnz .LBB0_192
	v_max_f32_e32 v52, 0, v52
	v_max_f32_e32 v48, 0, v48
	v_max_f32_e32 v53, 0, v53
	v_max_f32_e32 v49, 0, v49
	v_max_f32_e32 v54, 0, v54
	v_max_f32_e32 v50, 0, v50
	v_max_f32_e32 v55, 0, v55
	v_max_f32_e32 v51, 0, v51
	v_pk_mul_f32 v[52:53], v[52:53], v[52:53]
	v_pk_mul_f32 v[54:55], v[54:55], v[54:55]
	v_pk_mul_f32 v[48:49], v[48:49], v[48:49]
	v_pk_mul_f32 v[50:51], v[50:51], v[50:51]

; DI unsigned pk(float lo, float hi) { f32x2 v = {lo, hi}; bf2_t b = __builtin_convertvector(v, bf2_t); return __builtin_bit_cast(unsigned, b); }
; DI void gemm_epilogue(const GemmDesc& g, f32x4 (&acc)[2][2][4][2], int brow, int bcol, int wr, int wc, int fr, int fq) {
;     ...
;           const int row = rowb + ai * HALF + m * 16;
;           f32x4 v0 = acc[ai][bj][m][0], v1 = acc[ai][bj][m][1];
;           if (g.rowscale) { const float ru = gld<float>(g.rowscale + row); v0 = v0 * ru; v1 = v1 * ru; }
;           v0 = v0 + b0; v1 = v1 + b1;
;           if (epi == EPI_RELU2) {
; #pragma unroll
;             for (int j = 0; j < 4; ++j) { float r0 = fmaxf(v0[j], 0.f), r1 = fmaxf(v1[j], 0.f); v0[j] = r0 * r0; v1[j] = r1 * r1; }
;           }
;           u32x4 w; w.x = pk(v0[0], v0[1]); w.y = pk(v0[2], v0[3]); w.z = pk(v1[0], v1[1]); w.w = pk(v1[2], v1[3]);
.LBB0_194:
	v_pk_add_f32 v[46:47], v[70:71], v[46:47]
	v_pk_add_f32 v[44:45], v[68:69], v[44:45]
	v_pk_add_f32 v[42:43], v[66:67], v[42:43]
	s_and_b64 vcc, exec, s[46:47]
	v_pk_add_f32 v[40:41], v[64:65], v[40:41]
	s_cbranch_vccnz .LBB0_196
	v_max_f32_e32 v44, 0, v44
	v_max_f32_e32 v40, 0, v40
	v_max_f32_e32 v45, 0, v45
	v_max_f32_e32 v41, 0, v41
	v_max_f32_e32 v46, 0, v46
	v_max_f32_e32 v42, 0, v42
	v_max_f32_e32 v47, 0, v47
	v_max_f32_e32 v43, 0, v43
	v_pk_mul_f32 v[44:45], v[44:45], v[44:45]
	v_pk_mul_f32 v[46:47], v[46:47], v[46:47]
	v_pk_mul_f32 v[40:41], v[40:41], v[40:41]
	v_pk_mul_f32 v[42:43], v[42:43], v[42:43]

; DI unsigned pk(float lo, float hi) { f32x2 v = {lo, hi}; bf2_t b = __builtin_convertvector(v, bf2_t); return __builtin_bit_cast(unsigned, b); }
; DI void gemm_epilogue(const GemmDesc& g, f32x4 (&acc)[2][2][4][2], int brow, int bcol, int wr, int wc, int fr, int fq) {
;     ...
;           const int row = rowb + ai * HALF + m * 16;
;           f32x4 v0 = acc[ai][bj][m][0], v1 = acc[ai][bj][m][1];
;           if (g.rowscale) { const float ru = gld<float>(g.rowscale + row); v0 = v0 * ru; v1 = v1 * ru; }
;           v0 = v0 + b0; v1 = v1 + b1;
;           if (epi == EPI_RELU2) {
; #pragma unroll
;             for (int j = 0; j < 4; ++j) { float r0 = fmaxf(v0[j], 0.f), r1 = fmaxf(v1[j], 0.f); v0[j] = r0 * r0; v1[j] = r1 * r1; }
;           }
;           u32x4 w; w.x = pk(v0[0], v0[1]); w.y = pk(v0[2], v0[3]); w.z = pk(v1[0], v1[1]); w.w = pk(v1[2], v1[3]);
.LBB0_198:
	v_pk_add_f32 v[38:39], v[70:71], v[38:39]
	v_pk_add_f32 v[36:37], v[68:69], v[36:37]
	v_pk_add_f32 v[34:35], v[66:67], v[34:35]
	s_and_b64 vcc, exec, s[46:47]
	v_pk_add_f32 v[32:33], v[64:65], v[32:33]
	s_cbranch_vccnz .LBB0_200
	v_max_f32_e32 v36, 0, v36
	v_max_f32_e32 v32, 0, v32
	v_max_f32_e32 v37, 0, v37
	v_max_f32_e32 v33, 0, v33
	v_max_f32_e32 v38, 0, v38
	v_max_f32_e32 v34, 0, v34
	v_max_f32_e32 v39, 0, v39
	v_max_f32_e32 v35, 0, v35
	v_pk_mul_f32 v[36:37], v[36:37], v[36:37]
	v_pk_mul_f32 v[38:39], v[38:39], v[38:39]
	v_pk_mul_f32 v[32:33], v[32:33], v[32:33]
	v_pk_mul_f32 v[34:35], v[34:35], v[34:35]

; DI unsigned pk(float lo, float hi) { f32x2 v = {lo, hi}; bf2_t b = __builtin_convertvector(v, bf2_t); return __builtin_bit_cast(unsigned, b); }
; DI void gemm_epilogue(const GemmDesc& g, f32x4 (&acc)[2][2][4][2], int brow, int bcol, int wr, int wc, int fr, int fq) {
;     ...
;           const int row = rowb + ai * HALF + m * 16;
;           f32x4 v0 = acc[ai][bj][m][0], v1 = acc[ai][bj][m][1];
;           if (g.rowscale) { const float ru = gld<float>(g.rowscale + row); v0 = v0 * ru; v1 = v1 * ru; }
;           v0 = v0 + b0; v1 = v1 + b1;
;           if (epi == EPI_RELU2) {
; #pragma unroll
;             for (int j = 0; j < 4; ++j) { float r0 = fmaxf(v0[j], 0.f), r1 = fmaxf(v1[j], 0.f); v0[j] = r0 * r0; v1[j] = r1 * r1; }
;           }
;           u32x4 w; w.x = pk(v0[0], v0[1]); w.y = pk(v0[2], v0[3]); w.z = pk(v1[0], v1[1]); w.w = pk(v1[2], v1[3]);
.LBB0_202:
	v_pk_add_f32 v[30:31], v[70:71], v[30:31]
	v_pk_add_f32 v[28:29], v[68:69], v[28:29]
	v_pk_add_f32 v[26:27], v[66:67], v[26:27]
	s_and_b64 vcc, exec, s[46:47]
	v_pk_add_f32 v[24:25], v[64:65], v[24:25]
	s_cbranch_vccnz .LBB0_204
	v_max_f32_e32 v28, 0, v28
	v_max_f32_e32 v24, 0, v24
	v_max_f32_e32 v29, 0, v29
	v_max_f32_e32 v25, 0, v25
	v_max_f32_e32 v30, 0, v30
	v_max_f32_e32 v26, 0, v26
	v_max_f32_e32 v31, 0, v31
	v_max_f32_e32 v27, 0, v27
	v_pk_mul_f32 v[28:29], v[28:29], v[28:29]
	v_pk_mul_f32 v[30:31], v[30:31], v[30:31]
	v_pk_mul_f32 v[24:25], v[24:25], v[24:25]
	v_pk_mul_f32 v[26:27], v[26:27], v[26:27]

; DI unsigned pk(float lo, float hi) { f32x2 v = {lo, hi}; bf2_t b = __builtin_convertvector(v, bf2_t); return __builtin_bit_cast(unsigned, b); }
; DI void gemm_epilogue(const GemmDesc& g, f32x4 (&acc)[2][2][4][2], int brow, int bcol, int wr, int wc, int fr, int fq) {
;     ...
;           const int row = rowb + ai * HALF + m * 16;
;           f32x4 v0 = acc[ai][bj][m][0], v1 = acc[ai][bj][m][1];
;           if (g.rowscale) { const float ru = gld<float>(g.rowscale + row); v0 = v0 * ru; v1 = v1 * ru; }
;           v0 = v0 + b0; v1 = v1 + b1;
;           if (epi == EPI_RELU2) {
; #pragma unroll
;             for (int j = 0; j < 4; ++j) { float r0 = fmaxf(v0[j], 0.f), r1 = fmaxf(v1[j], 0.f); v0[j] = r0 * r0; v1[j] = r1 * r1; }
;           }
;           u32x4 w; w.x = pk(v0[0], v0[1]); w.y = pk(v0[2], v0[3]); w.z = pk(v1[0], v1[1]); w.w = pk(v1[2], v1[3]);
.LBB0_206:
	v_pk_add_f32 v[22:23], v[70:71], v[22:23]
	v_pk_add_f32 v[20:21], v[68:69], v[20:21]
	v_pk_add_f32 v[18:19], v[66:67], v[18:19]
	s_and_b64 vcc, exec, s[46:47]
	v_pk_add_f32 v[16:17], v[64:65], v[16:17]
	s_cbranch_vccnz .LBB0_208
	v_max_f32_e32 v20, 0, v20
	v_max_f32_e32 v16, 0, v16
	v_max_f32_e32 v21, 0, v21
	v_max_f32_e32 v17, 0, v17
	v_max_f32_e32 v22, 0, v22
	v_max_f32_e32 v18, 0, v18
	v_max_f32_e32 v23, 0, v23
	v_max_f32_e32 v19, 0, v19
	v_pk_mul_f32 v[20:21], v[20:21], v[20:21]
	v_pk_mul_f32 v[22:23], v[22:23], v[22:23]
	v_pk_mul_f32 v[16:17], v[16:17], v[16:17]
	v_pk_mul_f32 v[18:19], v[18:19], v[18:19]

; DI unsigned pk(float lo, float hi) { f32x2 v = {lo, hi}; bf2_t b = __builtin_convertvector(v, bf2_t); return __builtin_bit_cast(unsigned, b); }
; DI void gemm_epilogue(const GemmDesc& g, f32x4 (&acc)[2][2][4][2], int brow, int bcol, int wr, int wc, int fr, int fq) {
;     ...
;           const int row = rowb + ai * HALF + m * 16;
;           f32x4 v0 = acc[ai][bj][m][0], v1 = acc[ai][bj][m][1];
;           if (g.rowscale) { const float ru = gld<float>(g.rowscale + row); v0 = v0 * ru; v1 = v1 * ru; }
;           v0 = v0 + b0; v1 = v1 + b1;
;           if (epi == EPI_RELU2) {
; #pragma unroll
;             for (int j = 0; j < 4; ++j) { float r0 = fmaxf(v0[j], 0.f), r1 = fmaxf(v1[j], 0.f); v0[j] = r0 * r0; v1[j] = r1 * r1; }
;           }
;           u32x4 w; w.x = pk(v0[0], v0[1]); w.y = pk(v0[2], v0[3]); w.z = pk(v1[0], v1[1]); w.w = pk(v1[2], v1[3]);
.LBB0_210:
	v_pk_add_f32 v[14:15], v[70:71], v[14:15]
	v_pk_add_f32 v[12:13], v[68:69], v[12:13]
	v_pk_add_f32 v[10:11], v[66:67], v[10:11]
	s_and_b64 vcc, exec, s[46:47]
	v_pk_add_f32 v[8:9], v[64:65], v[8:9]
	s_cbranch_vccnz .LBB0_212
	v_max_f32_e32 v12, 0, v12
	v_max_f32_e32 v8, 0, v8
	v_max_f32_e32 v13, 0, v13
	v_max_f32_e32 v9, 0, v9
	v_max_f32_e32 v14, 0, v14
	v_max_f32_e32 v10, 0, v10
	v_max_f32_e32 v15, 0, v15
	v_max_f32_e32 v11, 0, v11
	v_pk_mul_f32 v[12:13], v[12:13], v[12:13]
	v_pk_mul_f32 v[14:15], v[14:15], v[14:15]
	v_pk_mul_f32 v[8:9], v[8:9], v[8:9]
	v_pk_mul_f32 v[10:11], v[10:11], v[10:11]

; DI unsigned pk(float lo, float hi) { f32x2 v = {lo, hi}; bf2_t b = __builtin_convertvector(v, bf2_t); return __builtin_bit_cast(unsigned, b); }
; DI void gemm_epilogue(const GemmDesc& g, f32x4 (&acc)[2][2][4][2], int brow, int bcol, int wr, int wc, int fr, int fq) {
;     ...
;           const int row = rowb + ai * HALF + m * 16;
;           f32x4 v0 = acc[ai][bj][m][0], v1 = acc[ai][bj][m][1];
;           if (g.rowscale) { const float ru = gld<float>(g.rowscale + row); v0 = v0 * ru; v1 = v1 * ru; }
;           v0 = v0 + b0; v1 = v1 + b1;
;           if (epi == EPI_RELU2) {
; #pragma unroll
;             for (int j = 0; j < 4; ++j) { float r0 = fmaxf(v0[j], 0.f), r1 = fmaxf(v1[j], 0.f); v0[j] = r0 * r0; v1[j] = r1 * r1; }
;           }
;           u32x4 w; w.x = pk(v0[0], v0[1]); w.y = pk(v0[2], v0[3]); w.z = pk(v1[0], v1[1]); w.w = pk(v1[2], v1[3]);
.LBB0_214:
	v_pk_add_f32 v[6:7], v[70:71], v[6:7]
	v_pk_add_f32 v[4:5], v[68:69], v[4:5]
	v_pk_add_f32 v[2:3], v[66:67], v[2:3]
	s_and_b64 vcc, exec, s[46:47]
	v_pk_add_f32 v[0:1], v[64:65], v[0:1]
	s_cbranch_vccnz .LBB0_216
	v_max_f32_e32 v4, 0, v4
	v_max_f32_e32 v0, 0, v0
	v_max_f32_e32 v5, 0, v5
	v_max_f32_e32 v1, 0, v1
	v_max_f32_e32 v6, 0, v6
	v_max_f32_e32 v2, 0, v2
	v_max_f32_e32 v7, 0, v7
	v_max_f32_e32 v3, 0, v3
	v_pk_mul_f32 v[4:5], v[4:5], v[4:5]
	v_pk_mul_f32 v[6:7], v[6:7], v[6:7]
	v_pk_mul_f32 v[0:1], v[0:1], v[0:1]
	v_pk_mul_f32 v[2:3], v[2:3], v[2:3]
